# attention loop: K/V tiles via LDS-DMA into two LDS banks, all four DMAs in step A's MFMA shadows, one barrier per iteration instead of two (on stack18)
# speedup vs baseline: 1.0007x; 1.0007x over previous
; #define LDSP __attribute__((address_space(3)))
; DI void attn_unit(const Params& p, int l, int b, int kvh, int qb, bool isctx, ldsp_t smem) {
;     int tid = threadIdx.x;
;     asm volatile("" : "+v"(tid));
;     const int wid = tid >> 6, lane = tid & 63, r = lane & 31, hh = lane >> 5;
;     const int head = kvh * 4 + (wid >> 1);
;     const int t0 = qb * 64 + (wid & 1) * 32;
;     const int nkeys = isctx ? CTXL : NKEY;
;     const bf16_t* Qp = isctx ? p.Qc + ((size_t)(b * 8 + head) * CTXL + t0) * 64 : p.Q + ((size_t)(b * 8 + head) * SEQ + t0) * 64;
;     const bf16_t* Kp = p.K + (size_t)(b * 2 + kvh) * NKEY * 64;
;     const bf16_t* Vp = p.Vt + (size_t)(b * 2 + kvh) * 64 * NKEY;
;     const int orow = isctx ? NLAT + b * CTXL + t0 : b * SEQ + t0;
;     bf16_t* Op = p.MIX + (size_t)orow * DM + head * 64;
;     const float cexp = p.smax[l] * LOG2E;
;     bf16x8 qf[4];
; #pragma unroll
;     for (int ks = 0; ks < 4; ++ks) qf[ks] = *(const bf16x8*)(Qp + (size_t)r * 64 + ks * 16 + 8 * hh);
;     f32x16 o[2];
; #pragma unroll
;     for (int i = 0; i < 16; ++i) { o[0][i] = 0.f; o[1][i] = 0.f; }
;     float rs0 = 0.f, rs1 = 0.f;
;     const int srow = tid >> 3, sch = tid & 7;
;     const int kdst = srow * 128 + ((sch ^ ((srow >> 1) & 7)) << 4);
;     const bf16_t* kg = Kp + (size_t)srow * 64 + sch * 8;
;     const bf16_t* vg = Vp + (size_t)srow * NKEY + sch * 8;
;     const int rsw = (r >> 1) & 7;
;     const int ntile = nkeys / 64;
;     ...
;     u32x4 kst, vst;
;     f32x16 sA[2], sB[2];
;     {
;         kst = *(const u32x4*)kg;
;         *(LDSP u32x4*)(smem + kdst) = kst;
;         kst = *(const u32x4*)(kg + (size_t)64 * 64);
;         vst = *(const u32x4*)vg;
;         __syncthreads();
;         ATT_QK(sA, smem);
;         *(LDSP u32x4*)(smem + 8192 + kdst) = kst;
;         *(LDSP u32x4*)(smem + 16384 + kdst) = vst;
;     }
.LBB0_163:
	v_mov_b32_e32 v24, v252
	s_lshl_b32 s9, s6, 2
	s_and_b32 s9, s9, 4
	v_ashrrev_i32_e32 v0, 7, v24
	v_add_u32_e32 v166, s9, v0
	s_lshl_b32 s9, s6, 3
	s_andn2_b32 s9, s9, 63
	v_lshrrev_b32_e32 v0, 1, v24
	v_and_or_b32 v144, v0, 32, s9
	s_and_b32 s9, s6, 7
	s_bfe_u32 s7, s6, 0x20001
	s_mul_i32 s98, s9, 0x88000
	v_ashrrev_i32_e32 v20, 3, v24
	s_add_u32 s10, s24, s98
	v_ashrrev_i32_e32 v21, 31, v20
	s_addc_u32 s11, s25, 0
	v_lshlrev_b32_e32 v10, 4, v24
	v_lshlrev_b64 v[0:1], 7, v[20:21]
	v_lshl_add_u64 v[0:1], s[10:11], 0, v[0:1]
	s_waitcnt lgkmcnt(5)
	v_and_b32_e32 v4, 0x70, v10
	s_waitcnt lgkmcnt(0)
	v_mov_b32_e32 v5, v193
	v_lshl_add_u64 v[146:147], v[0:1], 0, v[4:5]
	global_load_dwordx4 v[0:3], v[146:147], off
	global_load_dword v12, v193, s[4:5]
	v_lshl_add_u32 v6, s7, 3, v166
	v_ashrrev_i32_e32 v7, 31, v6
	v_ashrrev_i32_e32 v145, 31, v144
	v_lshlrev_b64 v[6:7], 19, v[6:7]
	v_and_b32_e32 v165, 31, v24
	v_lshlrev_b64 v[8:9], 7, v[144:145]
	v_lshl_add_u64 v[6:7], s[20:21], 0, v[6:7]
	v_bfe_u32 v164, v24, 5, 1
	v_lshl_add_u64 v[6:7], v[6:7], 0, v[8:9]
	v_lshlrev_b32_e32 v192, 7, v165
	v_lshl_add_u64 v[6:7], v[6:7], 0, v[192:193]
	v_lshlrev_b32_e32 v8, 4, v164
	v_mov_b32_e32 v9, v193
	v_lshl_add_u64 v[6:7], v[6:7], 0, v[8:9]
	global_load_dwordx4 v[112:115], v[6:7], off
	global_load_dwordx4 v[116:119], v[6:7], off offset:32
	global_load_dwordx4 v[120:123], v[6:7], off offset:64
	global_load_dwordx4 v[124:127], v[6:7], off offset:96
	v_lshrrev_b32_e32 v8, 5, v24
	v_bfe_u32 v16, v24, 1, 3
	s_add_u32 s10, s26, s98
	v_lshlrev_b32_e32 v9, 7, v20
	v_xor_b32_e32 v10, v10, v24
	v_bitop3_b32 v8, v8, v16, 1 bitop3:0x6c
	s_addc_u32 s11, s27, 0
	s_movk_i32 s9, 0x2000
	v_and_or_b32 v145, v10, s14, v9
	v_lshlrev_b32_e32 v167, 4, v8
	v_mov_b64_e32 v[8:9], s[10:11]
	s_movk_i32 s31, 0x2200
	v_add_co_u32_e32 v6, vcc, s9, v146
	v_mad_i64_i32 v[8:9], s[10:11], v20, s31, v[8:9]
	s_nop 0
	v_addc_co_u32_e32 v7, vcc, 0, v147, vcc
	v_lshl_add_u64 v[148:149], v[8:9], 0, v[4:5]
	global_load_dwordx4 v[4:7], v[6:7], off
	s_nop 0
	global_load_dwordx4 v[8:11], v[148:149], off
	v_or_b32_e32 v13, v192, v167
	v_mov_b64_e32 v[22:23], s[98:99]
	s_mov_b32 s9, -2
	s_movk_i32 s91, 0x2200
	s_waitcnt vmcnt(7)
	ds_write_b128 v145, v[0:3]
	s_waitcnt lgkmcnt(0)
	s_barrier
	ds_read_b128 v[0:3], v13
	s_waitcnt vmcnt(6)
	v_mul_f32_e32 v32, 0xbfb8aa3b, v12
	ds_read_b128 v[12:15], v13 offset:4096
	v_mov_b32_e32 v33, v32
	v_mov_b32_e32 v34, v32
	v_mov_b32_e32 v35, v32
	v_mov_b32_e32 v36, v32
	v_mov_b32_e32 v37, v32
	v_mov_b32_e32 v38, v32
	v_mov_b32_e32 v39, v32
	v_mov_b32_e32 v40, v32
	v_mov_b32_e32 v41, v32
	v_mov_b32_e32 v42, v32
	v_mov_b32_e32 v43, v32
	v_mov_b32_e32 v44, v32
	v_mov_b32_e32 v45, v32
	v_mov_b32_e32 v46, v32
	v_mov_b32_e32 v47, v32
	s_waitcnt vmcnt(5) lgkmcnt(1)
	s_nop 0
	v_mfma_f32_32x32x16_bf16 v[64:79], v[0:3], v[112:115], v[32:47]
	v_bitop3_b32 v0, v164, v16, 2 bitop3:0x36
	v_lshlrev_b32_e32 v168, 4, v0
	v_or_b32_e32 v17, v192, v168
	s_waitcnt lgkmcnt(0)
	v_mfma_f32_32x32x16_bf16 v[48:63], v[12:15], v[112:115], v[32:47]
	ds_read_b128 v[0:3], v17
	ds_read_b128 v[12:15], v17 offset:4096
	s_waitcnt vmcnt(4) lgkmcnt(1)
	v_mfma_f32_32x32x16_bf16 v[64:79], v[0:3], v[116:119], v[64:79]
	v_bitop3_b32 v0, v164, v16, 4 bitop3:0x36
	v_lshlrev_b32_e32 v169, 4, v0
	v_or_b32_e32 v17, v192, v169
	s_waitcnt lgkmcnt(0)
	v_mfma_f32_32x32x16_bf16 v[48:63], v[12:15], v[116:119], v[48:63]
	ds_read_b128 v[0:3], v17
	ds_read_b128 v[12:15], v17 offset:4096
	s_waitcnt vmcnt(3) lgkmcnt(1)
	v_mfma_f32_32x32x16_bf16 v[64:79], v[0:3], v[120:123], v[64:79]
	v_bitop3_b32 v0, v164, v16, 6 bitop3:0x36
	v_lshlrev_b32_e32 v170, 4, v0
	v_or_b32_e32 v21, v192, v170
	ds_read_b128 v[0:3], v21
	v_mov_b32_e32 v16, 0
	v_mov_b32_e32 v17, v16
	v_mov_b32_e32 v18, v16
	s_waitcnt lgkmcnt(1)
	v_mfma_f32_32x32x16_bf16 v[48:63], v[12:15], v[120:123], v[48:63]
	ds_read_b128 v[12:15], v21 offset:4096
	v_mov_b32_e32 v19, v16
	s_waitcnt vmcnt(1)
	ds_write_b128 v145, v[4:7] offset:8192
	s_waitcnt vmcnt(0)
	ds_write_b128 v145, v[8:11] offset:16384
	v_mov_b32_e32 v21, v16
	v_mov_b32_e32 v25, v16
	v_mov_b32_e32 v26, v16
	v_mov_b32_e32 v27, v16
	s_waitcnt lgkmcnt(3)
	v_mfma_f32_32x32x16_bf16 v[64:79], v[0:3], v[124:127], v[64:79]
	v_and_b32_e32 v2, 7, v24
	v_mad_i64_i32 v[0:1], s[10:11], v20, s31, v[22:23]
	v_lshl_or_b32 v0, v2, 4, v0
	v_lshl_add_u64 v[150:151], s[12:13], 0, v[0:1]
	v_mov_b32_e32 v20, v16
	v_mov_b32_e32 v22, v16
	s_waitcnt lgkmcnt(2)
	v_mfma_f32_32x32x16_bf16 v[48:63], v[12:15], v[124:127], v[48:63]
	v_mov_b32_e32 v23, v16
	v_mov_b32_e32 v24, v16
	v_mov_b32_e32 v28, v16
	v_mov_b32_e32 v29, v16
	v_mov_b32_e32 v30, v16
	v_mov_b32_e32 v31, v16
	v_mov_b32_e32 v0, v16
	v_mov_b32_e32 v1, v16
	v_mov_b32_e32 v2, v16
	v_mov_b32_e32 v3, v16
	v_mov_b32_e32 v4, v16
	v_mov_b32_e32 v5, v16
	v_mov_b32_e32 v6, v16
	v_mov_b32_e32 v7, v16
	v_mov_b32_e32 v8, v16
	v_mov_b32_e32 v9, v16
	v_mov_b32_e32 v10, v16
	v_mov_b32_e32 v11, v16
	v_mov_b32_e32 v12, v16
	v_mov_b32_e32 v13, v16
	v_mov_b32_e32 v14, v16
	v_mov_b32_e32 v15, v16
	v_mov_b32_e32 v136, v16
	v_mov_b32_e32 v137, v16
	v_and_b32_e32 v128, 7, v252
	v_bfe_u32 v129, v252, 4, 3
	v_xor_b32_e32 v129, v128, v129
	v_sub_u32_e32 v128, v129, v128
	v_lshlrev_b32_e32 v128, 4, v128
	v_ashrrev_i32_e32 v129, 31, v128
	v_lshrrev_b32_e32 v130, 6, v252
	v_lshlrev_b32_e32 v130, 10, v130
	v_lshl_add_u64 v[146:147], v[146:147], 0, v[128:129]
	v_lshl_add_u64 v[148:149], v[148:149], 0, v[128:129]
	v_lshl_add_u64 v[150:151], v[150:151], 0, v[128:129]
	v_readfirstlane_b32 s100, v130
	s_nop 3
	s_xor_b32 s101, s100, 0x18000
	v_mov_b32_e32 v128, 0x80
	v_mov_b32_e32 v129, 0
	v_lshl_add_u64 v[150:151], v[150:151], 0, v[128:129]
	v_lshl_add_u64 v[132:133], v[148:149], 0, v[128:129]
	v_mov_b32_e32 v128, 0x4000
	v_lshl_add_u64 v[130:131], v[146:147], 0, v[128:129]
	s_mov_b32 m0, s100
	s_waitcnt lgkmcnt(0)
	s_barrier
	global_load_lds_dwordx4 v[130:131], off
	s_add_u32 m0, s100, 0x6000
	s_nop 0
	global_load_lds_dwordx4 v[132:133], off
	.p2align	6
.LBB0_164:
	s_add_i32 s10, s9, 5
	s_min_u32 s10, s10, 0x43
	s_lshl_b32 s98, s10, 13
	v_lshl_add_u64 v[128:129], v[146:147], 0, s[98:99]
	s_add_i32 s11, s9, 6
	s_min_u32 s11, s11, 0x43
	s_lshl_b32 s98, s11, 13
	v_lshl_add_u64 v[130:131], v[146:147], 0, s[98:99]
	s_lshl_b32 s98, s10, 7
	v_lshl_add_u64 v[132:133], v[148:149], 0, s[98:99]
	s_waitcnt vmcnt(0)
	s_waitcnt lgkmcnt(0)
	s_barrier
	v_add_u32_e32 v171, v192, v167
	v_add_u32_e32 v172, v192, v168
	v_add_u32_e32 v142, v192, v169
	v_add_u32_e32 v143, v192, v170
	ds_read_b128 v[80:83], v171 offset:8192
	ds_read_b128 v[138:141], v171 offset:12288
	ds_read_b128 v[152:155], v172 offset:8192
	ds_read_b128 v[156:159], v172 offset:12288
	ds_read_b128 v[160:163], v142 offset:8192
	ds_read_b128 v[174:177], v142 offset:12288
	ds_read_b128 v[178:181], v143 offset:8192
	ds_read_b128 v[182:185], v143 offset:12288
	ds_read_b128 v[186:189], v171 offset:16384
	ds_read_b128 v[194:197], v171 offset:20480
	ds_read_b128 v[198:201], v172 offset:16384
	ds_read_b128 v[204:207], v172 offset:20480
	s_add_i32 s9, s9, 2
	s_waitcnt lgkmcnt(11)
	v_mfma_f32_32x32x16_bf16 v[96:111], v[80:83], v[112:115], v[32:47]
	v_xor_b32_e32 v192, 0x18000, v192
	v_exp_f32_e32 v64, v64
	v_exp_f32_e32 v65, v65
	v_exp_f32_e32 v66, v66
	v_exp_f32_e32 v67, v67
	v_exp_f32_e32 v68, v68
	v_exp_f32_e32 v69, v69
	v_exp_f32_e32 v74, v74
	s_add_u32 m0, s101, 0x2000
	s_waitcnt lgkmcnt(10)
	v_mfma_f32_32x32x16_bf16 v[80:95], v[138:141], v[112:115], v[32:47]
	global_load_lds_dwordx4 v[128:129], off
	v_exp_f32_e32 v138, v70
	v_exp_f32_e32 v139, v71
	v_exp_f32_e32 v140, v72
	v_exp_f32_e32 v141, v73
	v_exp_f32_e32 v75, v75
	v_exp_f32_e32 v70, v76
	v_exp_f32_e32 v71, v77
	s_add_u32 m0, s101, 0x4000
	s_waitcnt lgkmcnt(9)
	v_mfma_f32_32x32x16_bf16 v[96:111], v[152:155], v[116:119], v[96:111]
	global_load_lds_dwordx4 v[150:151], off
	v_exp_f32_e32 v152, v54
	v_exp_f32_e32 v153, v55
	v_cvt_pk_bf16_f32 v54, v68, v69
	v_cvt_pk_bf16_f32 v55, v138, v139
	v_exp_f32_e32 v72, v78
	v_exp_f32_e32 v73, v79
	v_exp_f32_e32 v48, v48
	s_mov_b32 m0, s101
	s_waitcnt lgkmcnt(8)
	v_mfma_f32_32x32x16_bf16 v[80:95], v[156:159], v[116:119], v[80:95]
	global_load_lds_dwordx4 v[130:131], off
	v_exp_f32_e32 v158, v52
	v_exp_f32_e32 v159, v53
	v_cvt_pk_bf16_f32 v52, v64, v65
	v_cvt_pk_bf16_f32 v53, v66, v67
	v_exp_f32_e32 v49, v49
	v_exp_f32_e32 v50, v50
	v_exp_f32_e32 v51, v51
	s_add_u32 m0, s101, 0x6000
	s_waitcnt lgkmcnt(3)
	v_mfma_f32_32x32x16_bf16 v[16:31], v[186:189], v[52:55], v[16:31]
	global_load_lds_dwordx4 v[132:133], off
	s_xor_b32 s101, s101, 0x18000
	v_exp_f32_e32 v154, v56
	v_exp_f32_e32 v155, v57
	v_exp_f32_e32 v156, v58
	v_exp_f32_e32 v157, v59
	v_pk_add_f32 v[56:57], v[136:137], v[64:65]
	s_waitcnt lgkmcnt(2)
	v_mfma_f32_32x32x16_bf16 v[0:15], v[194:197], v[52:55], v[0:15]
	v_cvt_pk_bf16_f32 v52, v140, v141
	v_cvt_pk_bf16_f32 v53, v74, v75
	v_cvt_pk_bf16_f32 v54, v70, v71
	v_cvt_pk_bf16_f32 v55, v72, v73
	v_add_f32_e64 v56, v66, v56
	v_add_f32_e64 v57, v67, v57
	v_pk_add_f32 v[56:57], v[68:69], v[56:57]
	v_mfma_f32_32x32x16_bf16 v[96:111], v[160:163], v[120:123], v[96:111]
	v_exp_f32_e32 v160, v60
	v_exp_f32_e32 v161, v61
	v_exp_f32_e32 v162, v62
	v_exp_f32_e32 v163, v63
	v_pk_add_f32 v[56:57], v[138:139], v[56:57]
	s_nop 0
	v_pk_add_f32 v[56:57], v[140:141], v[56:57]
	v_mfma_f32_32x32x16_bf16 v[80:95], v[174:177], v[120:123], v[80:95]
	v_add_f32_e64 v56, v74, v56
	v_add_f32_e64 v57, v75, v57
	v_add_f32_e64 v56, v70, v56
	v_add_f32_e64 v57, v71, v57
	v_add_f32_e64 v56, v72, v56
	v_add_f32_e64 v57, v73, v57
	s_waitcnt lgkmcnt(1)
	v_mfma_f32_32x32x16_bf16 v[16:31], v[198:201], v[52:55], v[16:31]
	s_waitcnt lgkmcnt(0)
	v_mfma_f32_32x32x16_bf16 v[0:15], v[204:207], v[52:55], v[0:15]
	v_cvt_pk_bf16_f32 v52, v48, v49
	v_cvt_pk_bf16_f32 v53, v50, v51
	v_cvt_pk_bf16_f32 v54, v158, v159
	v_cvt_pk_bf16_f32 v55, v152, v153
	v_add_f32_e64 v48, v48, v56
	v_add_f32_e64 v49, v49, v57
	v_pk_add_f32 v[190:191], v[50:51], v[48:49]
	v_mfma_f32_32x32x16_bf16 v[96:111], v[178:181], v[124:127], v[96:111]
	v_mfma_f32_32x32x16_bf16 v[80:95], v[182:185], v[124:127], v[80:95]
	ds_read_b128 v[174:177], v142 offset:16384
	ds_read_b128 v[178:181], v142 offset:20480
	ds_read_b128 v[182:185], v143 offset:16384
	ds_read_b128 v[210:213], v143 offset:20480
	s_waitcnt lgkmcnt(0)
	v_mfma_f32_32x32x16_bf16 v[16:31], v[174:177], v[52:55], v[16:31]
	v_mfma_f32_32x32x16_bf16 v[0:15], v[178:181], v[52:55], v[0:15]
	v_cvt_pk_bf16_f32 v52, v154, v155
	v_cvt_pk_bf16_f32 v53, v156, v157
	v_cvt_pk_bf16_f32 v54, v160, v161
	v_cvt_pk_bf16_f32 v55, v162, v163
	s_nop 1
	v_mfma_f32_32x32x16_bf16 v[16:31], v[182:185], v[52:55], v[16:31]
	v_mfma_f32_32x32x16_bf16 v[0:15], v[210:213], v[52:55], v[0:15]
	ds_read_b128 v[52:55], v171
	ds_read_b128 v[174:177], v172
	ds_read_b128 v[178:181], v142
	ds_read_b128 v[182:185], v143
	ds_read_b128 v[186:189], v171 offset:4096
	ds_read_b128 v[194:197], v172 offset:4096
	ds_read_b128 v[198:201], v142 offset:4096
	ds_read_b128 v[204:207], v143 offset:4096
	ds_read_b128 v[210:213], v171 offset:24576
	ds_read_b128 v[214:217], v171 offset:28672
	ds_read_b128 v[218:221], v172 offset:24576
	ds_read_b128 v[222:225], v172 offset:28672
	v_exp_f32_e32 v96, v96
	v_exp_f32_e32 v97, v97
	v_exp_f32_e32 v98, v98
	v_exp_f32_e32 v99, v99
	v_exp_f32_e32 v100, v100
	v_exp_f32_e32 v101, v101
	v_exp_f32_e32 v102, v102
	v_exp_f32_e32 v103, v103
	v_pk_add_f32 v[158:159], v[158:159], v[190:191]
	s_waitcnt lgkmcnt(11)
	v_mfma_f32_32x32x16_bf16 v[64:79], v[52:55], v[112:115], v[32:47]
	v_add_f32_e64 v152, v152, v158
	v_add_f32_e64 v153, v153, v159
	v_exp_f32_e32 v104, v104
	v_pk_add_f32 v[152:153], v[154:155], v[152:153]
	v_exp_f32_e32 v154, v80
	v_pk_add_f32 v[152:153], v[156:157], v[152:153]
	v_exp_f32_e32 v155, v81
	v_exp_f32_e32 v156, v82
	v_exp_f32_e32 v157, v83
	v_cvt_pk_bf16_f32 v80, v96, v97
	v_cvt_pk_bf16_f32 v81, v98, v99
	v_cvt_pk_bf16_f32 v82, v100, v101
	v_cvt_pk_bf16_f32 v83, v102, v103
	s_waitcnt lgkmcnt(7)
	v_mfma_f32_32x32x16_bf16 v[48:63], v[186:189], v[112:115], v[32:47]
	v_exp_f32_e32 v105, v105
	v_exp_f32_e32 v106, v106
	v_exp_f32_e32 v107, v107
	v_exp_f32_e32 v108, v108
	v_exp_f32_e32 v109, v109
	v_exp_f32_e32 v110, v110
	v_exp_f32_e32 v111, v111
	s_waitcnt lgkmcnt(3)
	v_mfma_f32_32x32x16_bf16 v[16:31], v[210:213], v[80:83], v[16:31]
	v_exp_f32_e32 v84, v84
	v_exp_f32_e32 v85, v85
	v_exp_f32_e32 v86, v86
	v_exp_f32_e32 v87, v87
	v_pk_add_f32 v[152:153], v[160:161], v[152:153]
	v_exp_f32_e32 v88, v88
	v_pk_add_f32 v[152:153], v[162:163], v[152:153]
	s_waitcnt lgkmcnt(2)
	v_mfma_f32_32x32x16_bf16 v[0:15], v[214:217], v[80:83], v[0:15]
	v_cvt_pk_bf16_f32 v80, v104, v105
	v_cvt_pk_bf16_f32 v81, v106, v107
	v_cvt_pk_bf16_f32 v82, v108, v109
	v_cvt_pk_bf16_f32 v83, v110, v111
	v_add_f32_e64 v152, v152, v96
	v_add_f32_e64 v153, v153, v97
	v_exp_f32_e32 v89, v89
	v_exp_f32_e32 v90, v90
	v_mfma_f32_32x32x16_bf16 v[64:79], v[174:177], v[116:119], v[64:79]
	v_exp_f32_e32 v91, v91
	v_exp_f32_e32 v92, v92
	v_exp_f32_e32 v93, v93
	v_exp_f32_e32 v94, v94
	v_exp_f32_e32 v95, v95
	v_pk_add_f32 v[152:153], v[98:99], v[152:153]
	v_lshl_add_u64 v[150:151], v[150:151], 0, s[96:97]
	s_waitcnt lgkmcnt(1)
	v_mfma_f32_32x32x16_bf16 v[16:31], v[218:221], v[80:83], v[16:31]
	v_add_f32_e64 v152, v100, v152
	v_add_f32_e64 v153, v101, v153
	s_cmpk_lt_u32 s9, 0x42
	v_add_f32_e64 v152, v102, v152
	v_add_f32_e64 v153, v103, v153
	v_pk_add_f32 v[152:153], v[104:105], v[152:153]
	s_waitcnt lgkmcnt(0)
	v_mfma_f32_32x32x16_bf16 v[0:15], v[222:225], v[80:83], v[0:15]
	v_cvt_pk_bf16_f32 v80, v154, v155
	v_cvt_pk_bf16_f32 v81, v156, v157
	v_cvt_pk_bf16_f32 v82, v84, v85
	v_cvt_pk_bf16_f32 v83, v86, v87
	v_mfma_f32_32x32x16_bf16 v[48:63], v[194:197], v[116:119], v[48:63]
	v_mfma_f32_32x32x16_bf16 v[64:79], v[178:181], v[120:123], v[64:79]
	ds_read_b128 v[172:175], v142 offset:24576
	ds_read_b128 v[176:179], v142 offset:28672
	ds_read_b128 v[136:139], v143 offset:24576
	ds_read_b128 v[140:143], v143 offset:28672
	s_waitcnt lgkmcnt(3)
	v_mfma_f32_32x32x16_bf16 v[16:31], v[172:175], v[80:83], v[16:31]
	s_waitcnt lgkmcnt(2)
	v_mfma_f32_32x32x16_bf16 v[0:15], v[176:179], v[80:83], v[0:15]
	v_cvt_pk_bf16_f32 v80, v88, v89
	v_cvt_pk_bf16_f32 v81, v90, v91
	v_cvt_pk_bf16_f32 v82, v92, v93
	v_cvt_pk_bf16_f32 v83, v94, v95
	v_mfma_f32_32x32x16_bf16 v[48:63], v[198:201], v[120:123], v[48:63]
	s_waitcnt lgkmcnt(1)
	v_mfma_f32_32x32x16_bf16 v[16:31], v[136:139], v[80:83], v[16:31]
	s_waitcnt lgkmcnt(0)
	v_mfma_f32_32x32x16_bf16 v[0:15], v[140:143], v[80:83], v[0:15]
	v_add_f32_e64 v80, v106, v152
	v_add_f32_e64 v81, v107, v153
	v_add_f32_e64 v80, v108, v80
	v_add_f32_e64 v81, v109, v81
	v_add_f32_e64 v80, v110, v80
	v_add_f32_e64 v81, v111, v81
	v_pk_add_f32 v[80:81], v[154:155], v[80:81]
	v_mfma_f32_32x32x16_bf16 v[64:79], v[182:185], v[124:127], v[64:79]
	v_add_f32_e64 v80, v156, v80
	v_add_f32_e64 v81, v157, v81
	v_add_f32_e64 v80, v84, v80
	v_add_f32_e64 v81, v85, v81
	v_add_f32_e64 v80, v86, v80
	v_add_f32_e64 v81, v87, v81
	v_pk_add_f32 v[80:81], v[88:89], v[80:81]
	v_mfma_f32_32x32x16_bf16 v[48:63], v[204:207], v[124:127], v[48:63]
	v_add_f32_e64 v80, v90, v80
	v_add_f32_e64 v81, v91, v81
	v_add_f32_e64 v80, v92, v80
	v_add_f32_e64 v81, v93, v81
	v_add_f32_e64 v136, v94, v80
	v_add_f32_e64 v137, v95, v81
	s_cbranch_scc1 .LBB0_164
; DI unsigned pk2(float a, float b) { f32x2 v = {a, b}; bf2_t r = __builtin_convertvector(v, bf2_t); return __builtin_bit_cast(unsigned, r); }
; DI void attn_unit(const Params& p, int l, int b, int kvh, int qb, bool isctx, ldsp_t smem) {
;     ...
;     const float lrun = rs0 + rs1;
;     const float ltot = lrun + __shfl_xor(lrun, 32);
;     const float inv = 1.f / ltot;
; #pragma unroll
;     for (int dt = 0; dt < 2; ++dt)
; #pragma unroll
;         for (int g4 = 0; g4 < 4; ++g4) {
;             u32x2 w; w[0] = pk2(o[dt][4 * g4 + 0] * inv, o[dt][4 * g4 + 1] * inv); w[1] = pk2(o[dt][4 * g4 + 2] * inv, o[dt][4 * g4 + 3] * inv);
;             *(u32x2*)(Op + (size_t)r * DM + dt * 32 + 8 * g4 + 4 * hh) = w;
;         }
;     __syncthreads();
	s_waitcnt vmcnt(0)
	v_lshrrev_b32_e32 v42, 6, v252
	v_mul_u32_u24_e32 v42, 0x1200, v42
	v_add_u32_e32 v42, 0x8000, v42
	v_and_b32_e32 v43, 31, v252
	v_mul_u32_u24_e32 v43, 0x90, v43
	v_bfe_u32 v40, v252, 5, 1
	v_lshl_add_u32 v40, v40, 3, v43
	v_add_u32_e32 v40, v42, v40
	v_bfe_u32 v43, v252, 3, 3
	v_mul_u32_u24_e32 v43, 0x90, v43
	v_and_b32_e32 v41, 7, v252
	v_lshl_add_u32 v41, v41, 4, v43
	v_add_u32_e32 v41, v42, v41
	v_lshl_add_u32 v32, s7, 12, v144
	v_ashrrev_i32_e32 v33, 31, v32
	v_lshlrev_b64 v[32:33], 11, v[32:33]
	v_lshlrev_b32_e32 v34, 6, v166
	v_lshl_add_u64 v[32:33], s[18:19], 0, v[32:33]
	v_ashrrev_i32_e32 v35, 31, v34
	v_cmp_lt_i32_e32 vcc, v209, v203
	v_lshl_add_u64 v[32:33], v[34:35], 1, v[32:33]
	v_add_f32_e32 v34, v137, v136
	v_cndmask_b32_e32 v35, v202, v209, vcc
	v_lshlrev_b32_e32 v35, 2, v35
	ds_bpermute_b32 v35, v35, v34
	v_bfe_u32 v192, v252, 3, 3
	v_lshlrev_b32_e32 v192, 11, v192
	v_lshl_add_u64 v[32:33], v[32:33], 0, v[192:193]
	v_and_b32_e32 v192, 7, v252
	v_lshlrev_b32_e32 v192, 4, v192
	v_lshl_add_u64 v[32:33], v[32:33], 0, v[192:193]
	s_waitcnt lgkmcnt(0)
	v_add_f32_e32 v34, v34, v35
	v_div_scale_f32 v35, s[10:11], v34, v34, 1.0
	v_rcp_f32_e32 v36, v35
	s_nop 0
	v_fma_f32 v37, -v35, v36, 1.0
	v_fmac_f32_e32 v36, v37, v36
	v_div_scale_f32 v37, vcc, 1.0, v34, 1.0
	v_mul_f32_e32 v38, v37, v36
	v_fma_f32 v39, -v35, v38, v37
	v_fmac_f32_e32 v38, v39, v36
	v_fma_f32 v35, -v35, v38, v37
	v_div_fmas_f32 v35, v35, v36, v38
	v_div_fixup_f32 v34, v35, v34, 1.0
	v_pk_mul_f32 v[16:17], v[16:17], v[34:35] op_sel_hi:[1,0]
	v_pk_mul_f32 v[18:19], v[18:19], v[34:35] op_sel_hi:[1,0]
	v_pk_mul_f32 v[0:1], v[0:1], v[34:35] op_sel_hi:[1,0]
	v_pk_mul_f32 v[2:3], v[2:3], v[34:35] op_sel_hi:[1,0]
	v_cvt_pk_bf16_f32 v16, v16, v17
	v_cvt_pk_bf16_f32 v17, v18, v19
	v_cvt_pk_bf16_f32 v0, v0, v1
	v_cvt_pk_bf16_f32 v1, v2, v3
	ds_write_b64 v40, v[16:17]
	v_pk_mul_f32 v[16:17], v[20:21], v[34:35] op_sel_hi:[1,0]
	v_pk_mul_f32 v[18:19], v[22:23], v[34:35] op_sel_hi:[1,0]
	ds_write_b64 v40, v[0:1] offset:64
	v_pk_mul_f32 v[0:1], v[4:5], v[34:35] op_sel_hi:[1,0]
	v_pk_mul_f32 v[2:3], v[6:7], v[34:35] op_sel_hi:[1,0]
	v_cvt_pk_bf16_f32 v16, v16, v17
	v_cvt_pk_bf16_f32 v17, v18, v19
	v_cvt_pk_bf16_f32 v0, v0, v1
	v_cvt_pk_bf16_f32 v1, v2, v3
	ds_write_b64 v40, v[16:17] offset:16
	v_pk_mul_f32 v[16:17], v[24:25], v[34:35] op_sel_hi:[1,0]
	v_pk_mul_f32 v[18:19], v[26:27], v[34:35] op_sel_hi:[1,0]
	ds_write_b64 v40, v[0:1] offset:80
	v_pk_mul_f32 v[0:1], v[8:9], v[34:35] op_sel_hi:[1,0]
	v_pk_mul_f32 v[2:3], v[10:11], v[34:35] op_sel_hi:[1,0]
	v_cvt_pk_bf16_f32 v16, v16, v17
	v_cvt_pk_bf16_f32 v17, v18, v19
	v_cvt_pk_bf16_f32 v0, v0, v1
	v_cvt_pk_bf16_f32 v1, v2, v3
	ds_write_b64 v40, v[16:17] offset:32
	v_pk_mul_f32 v[16:17], v[28:29], v[34:35] op_sel_hi:[1,0]
	v_pk_mul_f32 v[18:19], v[30:31], v[34:35] op_sel_hi:[1,0]
	ds_write_b64 v40, v[0:1] offset:96
	v_pk_mul_f32 v[0:1], v[12:13], v[34:35] op_sel_hi:[1,0]
	v_pk_mul_f32 v[2:3], v[14:15], v[34:35] op_sel_hi:[1,0]
	v_cvt_pk_bf16_f32 v16, v16, v17
	v_cvt_pk_bf16_f32 v17, v18, v19
	v_cvt_pk_bf16_f32 v0, v0, v1
	v_cvt_pk_bf16_f32 v1, v2, v3
	ds_write_b64 v40, v[16:17] offset:48
	ds_write_b64 v40, v[0:1] offset:112
	ds_read_b128 v[44:47], v41
	ds_read_b128 v[48:51], v41 offset:1152
	ds_read_b128 v[52:55], v41 offset:2304
	ds_read_b128 v[56:59], v41 offset:3456
	v_mov_b32_e32 v192, 0x4000
	v_lshl_add_u64 v[60:61], v[32:33], 0, v[192:193]
	v_lshl_add_u64 v[62:63], v[60:61], 0, v[192:193]
	v_lshl_add_u64 v[64:65], v[62:63], 0, v[192:193]
	s_waitcnt lgkmcnt(0)
	global_store_dwordx4 v[32:33], v[44:47], off sc1
	global_store_dwordx4 v[60:61], v[48:51], off sc1
	global_store_dwordx4 v[62:63], v[52:55], off sc1
	global_store_dwordx4 v[64:65], v[56:59], off sc1
	s_barrier
	s_load_dword s7, s[88:89], 0x0
	s_waitcnt lgkmcnt(0)
	s_add_i32 s6, s7, s6
	s_cmpk_gt_i32 s6, 0x1ff
	s_cbranch_scc0 .LBB0_163
